# v31: v11 + streaming phases given memory-level parallelism: phase_cvt_p issues its 16 loads together, phase_final_norm software-pipelined over two row register sets (fast paths for the 256-workgroup g
# speedup vs baseline: 1.0010x; 1.0010x over previous
.LBB0_159:
	s_or_b64 exec, exec, s[12:13]
	s_mov_b32 s3, 0
	s_lshl_b64 s[0:1], s[2:3], 9
	v_mov_b32_e32 v4, v234
	v_writelane_b32 v253, s0, 12
	v_ashrrev_i32_e32 v5, 31, v4
	s_nop 0
	v_writelane_b32 v253, s1, 13
	v_lshl_add_u64 v[2:3], s[0:1], 0, v[4:5]
	s_mov_b64 s[0:1], 0x200000
	v_cmp_gt_u64_e32 vcc, s[0:1], v[2:3]
	s_and_saveexec_b64 s[0:1], vcc
	s_cbranch_execz .LBB0_162
	s_mov_b32 s14, s46
	s_mov_b32 s15, s3
	v_readlane_b32 s16, v252, 38
	s_lshl_b64 s[4:5], s[14:15], 9
	s_lshl_b64 s[12:13], s[2:3], 13
	v_readlane_b32 s18, v252, 40
	v_readlane_b32 s19, v252, 41
	s_add_u32 s12, s18, s12
	v_readlane_b32 s17, v252, 39
	s_addc_u32 s13, s19, s13
	v_lshl_add_u64 v[6:7], v[4:5], 4, s[12:13]
	s_lshl_b64 s[12:13], s[14:15], 13
	s_lshl_b64 s[16:17], s[2:3], 12
	s_add_u32 s16, s10, s16
	s_addc_u32 s17, s11, s17
	v_lshl_add_u64 v[4:5], v[4:5], 3, s[16:17]
	s_mov_b64 s[16:17], 0x1c300000
	v_lshl_add_u64 v[4:5], v[4:5], 0, s[16:17]
	s_lshl_b64 s[14:15], s[14:15], 12
	s_mov_b64 s[16:17], 0
	s_mov_b64 s[18:19], 0x1fffff
	v_readlane_b32 s20, v252, 42
	v_readlane_b32 s21, v252, 43
	v_readlane_b32 s22, v252, 44
	v_readlane_b32 s23, v252, 45
	v_readlane_b32 s24, v252, 46
	v_readlane_b32 s25, v252, 47
	v_readlane_b32 s26, v252, 48
	v_readlane_b32 s27, v252, 49
	v_readlane_b32 s28, v252, 50
	v_readlane_b32 s29, v252, 51
	v_readlane_b32 s30, v252, 52
	v_readlane_b32 s31, v252, 53
	s_cmp_lg_u32 s46, 0x100
	s_cbranch_scc1 .LBB0_161
	global_load_dwordx4 v[64:67], v[6:7], off
	v_lshl_add_u64 v[6:7], v[6:7], 0, s[12:13]
	global_load_dwordx4 v[68:71], v[6:7], off
	v_lshl_add_u64 v[6:7], v[6:7], 0, s[12:13]
	global_load_dwordx4 v[72:75], v[6:7], off
	v_lshl_add_u64 v[6:7], v[6:7], 0, s[12:13]
	global_load_dwordx4 v[76:79], v[6:7], off
	v_lshl_add_u64 v[6:7], v[6:7], 0, s[12:13]
	global_load_dwordx4 v[80:83], v[6:7], off
	v_lshl_add_u64 v[6:7], v[6:7], 0, s[12:13]
	global_load_dwordx4 v[84:87], v[6:7], off
	v_lshl_add_u64 v[6:7], v[6:7], 0, s[12:13]
	global_load_dwordx4 v[88:91], v[6:7], off
	v_lshl_add_u64 v[6:7], v[6:7], 0, s[12:13]
	global_load_dwordx4 v[92:95], v[6:7], off
	v_lshl_add_u64 v[6:7], v[6:7], 0, s[12:13]
	global_load_dwordx4 v[96:99], v[6:7], off
	v_lshl_add_u64 v[6:7], v[6:7], 0, s[12:13]
	global_load_dwordx4 v[100:103], v[6:7], off
	v_lshl_add_u64 v[6:7], v[6:7], 0, s[12:13]
	global_load_dwordx4 v[104:107], v[6:7], off
	v_lshl_add_u64 v[6:7], v[6:7], 0, s[12:13]
	global_load_dwordx4 v[108:111], v[6:7], off
	v_lshl_add_u64 v[6:7], v[6:7], 0, s[12:13]
	global_load_dwordx4 v[112:115], v[6:7], off
	v_lshl_add_u64 v[6:7], v[6:7], 0, s[12:13]
	global_load_dwordx4 v[116:119], v[6:7], off
	v_lshl_add_u64 v[6:7], v[6:7], 0, s[12:13]
	global_load_dwordx4 v[120:123], v[6:7], off
	v_lshl_add_u64 v[6:7], v[6:7], 0, s[12:13]
	global_load_dwordx4 v[124:127], v[6:7], off
	s_waitcnt vmcnt(15)
	v_cvt_pk_bf16_f32 v64, v64, v65
	v_cvt_pk_bf16_f32 v65, v66, v67
	global_store_dwordx2 v[4:5], v[64:65], off
	v_lshl_add_u64 v[4:5], v[4:5], 0, s[14:15]
	s_waitcnt vmcnt(15)
	v_cvt_pk_bf16_f32 v68, v68, v69
	v_cvt_pk_bf16_f32 v69, v70, v71
	global_store_dwordx2 v[4:5], v[68:69], off
	v_lshl_add_u64 v[4:5], v[4:5], 0, s[14:15]
	s_waitcnt vmcnt(15)
	v_cvt_pk_bf16_f32 v72, v72, v73
	v_cvt_pk_bf16_f32 v73, v74, v75
	global_store_dwordx2 v[4:5], v[72:73], off
	v_lshl_add_u64 v[4:5], v[4:5], 0, s[14:15]
	s_waitcnt vmcnt(15)
	v_cvt_pk_bf16_f32 v76, v76, v77
	v_cvt_pk_bf16_f32 v77, v78, v79
	global_store_dwordx2 v[4:5], v[76:77], off
	v_lshl_add_u64 v[4:5], v[4:5], 0, s[14:15]
	s_waitcnt vmcnt(15)
	v_cvt_pk_bf16_f32 v80, v80, v81
	v_cvt_pk_bf16_f32 v81, v82, v83
	global_store_dwordx2 v[4:5], v[80:81], off
	v_lshl_add_u64 v[4:5], v[4:5], 0, s[14:15]
	s_waitcnt vmcnt(15)
	v_cvt_pk_bf16_f32 v84, v84, v85
	v_cvt_pk_bf16_f32 v85, v86, v87
	global_store_dwordx2 v[4:5], v[84:85], off
	v_lshl_add_u64 v[4:5], v[4:5], 0, s[14:15]
	s_waitcnt vmcnt(15)
	v_cvt_pk_bf16_f32 v88, v88, v89
	v_cvt_pk_bf16_f32 v89, v90, v91
	global_store_dwordx2 v[4:5], v[88:89], off
	v_lshl_add_u64 v[4:5], v[4:5], 0, s[14:15]
	s_waitcnt vmcnt(15)
	v_cvt_pk_bf16_f32 v92, v92, v93
	v_cvt_pk_bf16_f32 v93, v94, v95
	global_store_dwordx2 v[4:5], v[92:93], off
	v_lshl_add_u64 v[4:5], v[4:5], 0, s[14:15]
	s_waitcnt vmcnt(15)
	v_cvt_pk_bf16_f32 v96, v96, v97
	v_cvt_pk_bf16_f32 v97, v98, v99
	global_store_dwordx2 v[4:5], v[96:97], off
	v_lshl_add_u64 v[4:5], v[4:5], 0, s[14:15]
	s_waitcnt vmcnt(15)
	v_cvt_pk_bf16_f32 v100, v100, v101
	v_cvt_pk_bf16_f32 v101, v102, v103
	global_store_dwordx2 v[4:5], v[100:101], off
	v_lshl_add_u64 v[4:5], v[4:5], 0, s[14:15]
	s_waitcnt vmcnt(15)
	v_cvt_pk_bf16_f32 v104, v104, v105
	v_cvt_pk_bf16_f32 v105, v106, v107
	global_store_dwordx2 v[4:5], v[104:105], off
	v_lshl_add_u64 v[4:5], v[4:5], 0, s[14:15]
	s_waitcnt vmcnt(15)
	v_cvt_pk_bf16_f32 v108, v108, v109
	v_cvt_pk_bf16_f32 v109, v110, v111
	global_store_dwordx2 v[4:5], v[108:109], off
	v_lshl_add_u64 v[4:5], v[4:5], 0, s[14:15]
	s_waitcnt vmcnt(15)
	v_cvt_pk_bf16_f32 v112, v112, v113
	v_cvt_pk_bf16_f32 v113, v114, v115
	global_store_dwordx2 v[4:5], v[112:113], off
	v_lshl_add_u64 v[4:5], v[4:5], 0, s[14:15]
	s_waitcnt vmcnt(15)
	v_cvt_pk_bf16_f32 v116, v116, v117
	v_cvt_pk_bf16_f32 v117, v118, v119
	global_store_dwordx2 v[4:5], v[116:117], off
	v_lshl_add_u64 v[4:5], v[4:5], 0, s[14:15]
	s_waitcnt vmcnt(15)
	v_cvt_pk_bf16_f32 v120, v120, v121
	v_cvt_pk_bf16_f32 v121, v122, v123
	global_store_dwordx2 v[4:5], v[120:121], off
	v_lshl_add_u64 v[4:5], v[4:5], 0, s[14:15]
	s_waitcnt vmcnt(15)
	v_cvt_pk_bf16_f32 v124, v124, v125
	v_cvt_pk_bf16_f32 v125, v126, v127
	global_store_dwordx2 v[4:5], v[124:125], off
	s_branch .LBB0_162

.LBB0_870:
	s_or_b64 exec, exec, s[34:35]
	v_readlane_b32 s0, v255, 28
	s_cmp_eq_u32 s0, 3
	v_readlane_b32 s1, v255, 29
	s_cbranch_scc1 .LBB0_875
	v_mov_b32_e32 v4, v234
	v_readlane_b32 s2, v253, 12
	v_readlane_b32 s3, v253, 13
	v_ashrrev_i32_e32 v5, 31, v4
	s_nop 0
	v_lshl_add_u64 v[0:1], s[2:3], 0, v[4:5]
	s_mov_b64 s[2:3], 0x200000
	v_cmp_gt_u64_e32 vcc, s[2:3], v[0:1]
	s_and_saveexec_b64 s[2:3], vcc
	v_readlane_b32 s0, v254, 47
	v_readlane_b32 s12, v255, 0
	v_readlane_b32 s16, v255, 20
	v_readlane_b32 s1, v254, 48
	v_readlane_b32 s13, v255, 1
	v_readlane_b32 s17, v255, 21
	s_cbranch_execz .LBB0_874
	v_readlane_b32 s4, v254, 62
	v_readlane_b32 s5, v254, 63
	s_nop 1
	v_lshl_add_u64 v[2:3], v[4:5], 4, s[4:5]
	v_readlane_b32 s4, v255, 2
	v_readlane_b32 s5, v255, 3
	s_nop 1
	v_lshl_add_u64 v[4:5], v[4:5], 3, s[4:5]
	s_mov_b64 s[4:5], 0
	s_cmp_lg_u32 s46, 0x100
	s_cbranch_scc1 .LBB0_873
	global_load_dwordx4 v[64:67], v[2:3], off
	v_lshl_add_u64 v[2:3], v[2:3], 0, s[12:13]
	global_load_dwordx4 v[68:71], v[2:3], off
	v_lshl_add_u64 v[2:3], v[2:3], 0, s[12:13]
	global_load_dwordx4 v[72:75], v[2:3], off
	v_lshl_add_u64 v[2:3], v[2:3], 0, s[12:13]
	global_load_dwordx4 v[76:79], v[2:3], off
	v_lshl_add_u64 v[2:3], v[2:3], 0, s[12:13]
	global_load_dwordx4 v[80:83], v[2:3], off
	v_lshl_add_u64 v[2:3], v[2:3], 0, s[12:13]
	global_load_dwordx4 v[84:87], v[2:3], off
	v_lshl_add_u64 v[2:3], v[2:3], 0, s[12:13]
	global_load_dwordx4 v[88:91], v[2:3], off
	v_lshl_add_u64 v[2:3], v[2:3], 0, s[12:13]
	global_load_dwordx4 v[92:95], v[2:3], off
	v_lshl_add_u64 v[2:3], v[2:3], 0, s[12:13]
	global_load_dwordx4 v[96:99], v[2:3], off
	v_lshl_add_u64 v[2:3], v[2:3], 0, s[12:13]
	global_load_dwordx4 v[100:103], v[2:3], off
	v_lshl_add_u64 v[2:3], v[2:3], 0, s[12:13]
	global_load_dwordx4 v[104:107], v[2:3], off
	v_lshl_add_u64 v[2:3], v[2:3], 0, s[12:13]
	global_load_dwordx4 v[108:111], v[2:3], off
	v_lshl_add_u64 v[2:3], v[2:3], 0, s[12:13]
	global_load_dwordx4 v[112:115], v[2:3], off
	v_lshl_add_u64 v[2:3], v[2:3], 0, s[12:13]
	global_load_dwordx4 v[116:119], v[2:3], off
	v_lshl_add_u64 v[2:3], v[2:3], 0, s[12:13]
	global_load_dwordx4 v[120:123], v[2:3], off
	v_lshl_add_u64 v[2:3], v[2:3], 0, s[12:13]
	global_load_dwordx4 v[124:127], v[2:3], off
	s_waitcnt vmcnt(15)
	v_cvt_pk_bf16_f32 v64, v64, v65
	v_cvt_pk_bf16_f32 v65, v66, v67
	global_store_dwordx2 v[4:5], v[64:65], off
	v_lshl_add_u64 v[4:5], v[4:5], 0, s[16:17]
	s_waitcnt vmcnt(15)
	v_cvt_pk_bf16_f32 v68, v68, v69
	v_cvt_pk_bf16_f32 v69, v70, v71
	global_store_dwordx2 v[4:5], v[68:69], off
	v_lshl_add_u64 v[4:5], v[4:5], 0, s[16:17]
	s_waitcnt vmcnt(15)
	v_cvt_pk_bf16_f32 v72, v72, v73
	v_cvt_pk_bf16_f32 v73, v74, v75
	global_store_dwordx2 v[4:5], v[72:73], off
	v_lshl_add_u64 v[4:5], v[4:5], 0, s[16:17]
	s_waitcnt vmcnt(15)
	v_cvt_pk_bf16_f32 v76, v76, v77
	v_cvt_pk_bf16_f32 v77, v78, v79
	global_store_dwordx2 v[4:5], v[76:77], off
	v_lshl_add_u64 v[4:5], v[4:5], 0, s[16:17]
	s_waitcnt vmcnt(15)
	v_cvt_pk_bf16_f32 v80, v80, v81
	v_cvt_pk_bf16_f32 v81, v82, v83
	global_store_dwordx2 v[4:5], v[80:81], off
	v_lshl_add_u64 v[4:5], v[4:5], 0, s[16:17]
	s_waitcnt vmcnt(15)
	v_cvt_pk_bf16_f32 v84, v84, v85
	v_cvt_pk_bf16_f32 v85, v86, v87
	global_store_dwordx2 v[4:5], v[84:85], off
	v_lshl_add_u64 v[4:5], v[4:5], 0, s[16:17]
	s_waitcnt vmcnt(15)
	v_cvt_pk_bf16_f32 v88, v88, v89
	v_cvt_pk_bf16_f32 v89, v90, v91
	global_store_dwordx2 v[4:5], v[88:89], off
	v_lshl_add_u64 v[4:5], v[4:5], 0, s[16:17]
	s_waitcnt vmcnt(15)
	v_cvt_pk_bf16_f32 v92, v92, v93
	v_cvt_pk_bf16_f32 v93, v94, v95
	global_store_dwordx2 v[4:5], v[92:93], off
	v_lshl_add_u64 v[4:5], v[4:5], 0, s[16:17]
	s_waitcnt vmcnt(15)
	v_cvt_pk_bf16_f32 v96, v96, v97
	v_cvt_pk_bf16_f32 v97, v98, v99
	global_store_dwordx2 v[4:5], v[96:97], off
	v_lshl_add_u64 v[4:5], v[4:5], 0, s[16:17]
	s_waitcnt vmcnt(15)
	v_cvt_pk_bf16_f32 v100, v100, v101
	v_cvt_pk_bf16_f32 v101, v102, v103
	global_store_dwordx2 v[4:5], v[100:101], off
	v_lshl_add_u64 v[4:5], v[4:5], 0, s[16:17]
	s_waitcnt vmcnt(15)
	v_cvt_pk_bf16_f32 v104, v104, v105
	v_cvt_pk_bf16_f32 v105, v106, v107
	global_store_dwordx2 v[4:5], v[104:105], off
	v_lshl_add_u64 v[4:5], v[4:5], 0, s[16:17]
	s_waitcnt vmcnt(15)
	v_cvt_pk_bf16_f32 v108, v108, v109
	v_cvt_pk_bf16_f32 v109, v110, v111
	global_store_dwordx2 v[4:5], v[108:109], off
	v_lshl_add_u64 v[4:5], v[4:5], 0, s[16:17]
	s_waitcnt vmcnt(15)
	v_cvt_pk_bf16_f32 v112, v112, v113
	v_cvt_pk_bf16_f32 v113, v114, v115
	global_store_dwordx2 v[4:5], v[112:113], off
	v_lshl_add_u64 v[4:5], v[4:5], 0, s[16:17]
	s_waitcnt vmcnt(15)
	v_cvt_pk_bf16_f32 v116, v116, v117
	v_cvt_pk_bf16_f32 v117, v118, v119
	global_store_dwordx2 v[4:5], v[116:117], off
	v_lshl_add_u64 v[4:5], v[4:5], 0, s[16:17]
	s_waitcnt vmcnt(15)
	v_cvt_pk_bf16_f32 v120, v120, v121
	v_cvt_pk_bf16_f32 v121, v122, v123
	global_store_dwordx2 v[4:5], v[120:121], off
	v_lshl_add_u64 v[4:5], v[4:5], 0, s[16:17]
	s_waitcnt vmcnt(15)
	v_cvt_pk_bf16_f32 v124, v124, v125
	v_cvt_pk_bf16_f32 v125, v126, v127
	global_store_dwordx2 v[4:5], v[124:125], off
	s_branch .LBB0_874

.LBB0_1108:
	v_mov_b32_e32 v18, v234
	v_readlane_b32 s0, v253, 9
	v_ashrrev_i32_e32 v0, 6, v234
	s_nop 0
	v_add_u32_e32 v16, s0, v0
	s_mov_b32 s0, 0x8000
	v_cmp_gt_i32_e32 vcc, s0, v16
	s_and_saveexec_b64 s[0:1], vcc
	v_readlane_b32 s6, v253, 10
	v_readlane_b32 s7, v253, 11
	s_cbranch_execz .LBB0_1111
	v_lshlrev_b32_e32 v0, 4, v18
	v_readlane_b32 s12, v252, 4
	v_and_b32_e32 v17, 0x3f0, v0
	v_readlane_b32 s26, v252, 18
	v_readlane_b32 s27, v252, 19
	s_nop 4
	global_load_dwordx4 v[0:3], v17, s[26:27]
	global_load_dwordx4 v[4:7], v17, s[26:27] offset:1024
	global_load_dwordx4 v[8:11], v17, s[26:27] offset:2048
	global_load_dwordx4 v[12:15], v17, s[26:27] offset:3072
	v_and_b32_e32 v17, 64, v237
	v_add_u32_e32 v17, 64, v17
	v_xor_b32_e32 v19, 32, v237
	v_cmp_lt_i32_e32 vcc, v19, v17
	s_mov_b64 s[0:1], 0xc00
	s_ashr_i32 s7, s6, 31
	v_cndmask_b32_e32 v19, v237, v19, vcc
	v_lshlrev_b32_e32 v20, 2, v19
	v_xor_b32_e32 v19, 16, v237
	v_cmp_lt_i32_e32 vcc, v19, v17
	v_readlane_b32 s14, v252, 6
	v_readlane_b32 s15, v252, 7
	v_cndmask_b32_e32 v19, v237, v19, vcc
	v_lshlrev_b32_e32 v21, 2, v19
	v_xor_b32_e32 v19, 8, v237
	v_cmp_lt_i32_e32 vcc, v19, v17
	s_mov_b64 s[2:3], 0
	s_movk_i32 s4, 0x7fff
	v_cndmask_b32_e32 v19, v237, v19, vcc
	v_lshlrev_b32_e32 v22, 2, v19
	v_xor_b32_e32 v19, 4, v237
	v_cmp_lt_i32_e32 vcc, v19, v17
	v_readlane_b32 s13, v252, 5
	v_readlane_b32 s16, v252, 8
	v_cndmask_b32_e32 v19, v237, v19, vcc
	v_lshlrev_b32_e32 v23, 2, v19
	v_xor_b32_e32 v19, 2, v237
	v_cmp_lt_i32_e32 vcc, v19, v17
	v_readlane_b32 s17, v252, 9
	v_readlane_b32 s18, v252, 10
	v_cndmask_b32_e32 v19, v237, v19, vcc
	v_lshlrev_b32_e32 v24, 2, v19
	v_xor_b32_e32 v19, 1, v237
	v_cmp_lt_i32_e32 vcc, v19, v17
	v_readlane_b32 s19, v252, 11
	v_readlane_b32 s20, v252, 12
	v_cndmask_b32_e32 v17, v237, v19, vcc
	v_lshlrev_b32_e32 v25, 2, v17
	v_ashrrev_i32_e32 v17, 31, v16
	v_lshlrev_b64 v[26:27], 12, v[16:17]
	v_and_b32_e32 v17, 63, v18
	v_lshl_or_b32 v26, v17, 4, v26
	v_lshl_add_u64 v[18:19], s[8:9], 0, v[26:27]
	v_lshl_add_u64 v[18:19], v[18:19], 0, s[0:1]
	s_lshl_b64 s[0:1], s[6:7], 12
	v_mov_b32_e32 v17, 0x358637bd
	v_readlane_b32 s21, v252, 13
	v_readlane_b32 s22, v252, 14
	v_readlane_b32 s23, v252, 15
	v_readlane_b32 s24, v252, 16
	v_readlane_b32 s25, v252, 17
	s_mov_b64 s[14:15], s[26:27]
	s_cmpk_lg_i32 s6, 0x800
	s_cbranch_scc1 .LBB0_1110
	global_load_dwordx4 v[26:29], v[18:19], off offset:-3072
	global_load_dwordx4 v[30:33], v[18:19], off offset:-2048
	global_load_dwordx4 v[34:37], v[18:19], off offset:-1024
	global_load_dwordx4 v[38:41], v[18:19], off
	v_lshl_add_u64 v[68:69], v[18:19], 0, s[0:1]
	global_load_dwordx4 v[52:55], v[68:69], off offset:-3072
	global_load_dwordx4 v[56:59], v[68:69], off offset:-2048
	global_load_dwordx4 v[60:63], v[68:69], off offset:-1024
	global_load_dwordx4 v[64:67], v[68:69], off
	s_waitcnt vmcnt(4)
	v_mul_f32_e32 v50, v27, v27
	v_mul_f32_e32 v51, v31, v31
	v_mov_b32_e32 v44, v35
	v_mov_b32_e32 v45, v39
	v_mov_b32_e32 v42, v34
	v_mov_b32_e32 v43, v38
	v_fmac_f32_e32 v50, v26, v26
	v_fmac_f32_e32 v51, v30, v30
	v_pk_mul_f32 v[44:45], v[44:45], v[44:45]
	v_mov_b32_e32 v46, v36
	v_mov_b32_e32 v47, v40
	v_fmac_f32_e32 v50, v28, v28
	v_fmac_f32_e32 v51, v32, v32
	v_pk_fma_f32 v[42:43], v[42:43], v[42:43], v[44:45]
	v_mov_b32_e32 v48, v37
	v_mov_b32_e32 v49, v41
	v_fmac_f32_e32 v50, v29, v29
	v_fmac_f32_e32 v51, v33, v33
	v_pk_fma_f32 v[42:43], v[46:47], v[46:47], v[42:43]
	v_add_f32_e32 v44, v50, v51
	v_pk_fma_f32 v[42:43], v[48:49], v[48:49], v[42:43]
	s_nop 0
	v_add_f32_e32 v42, v44, v42
	v_add_f32_e32 v42, v42, v43
	ds_bpermute_b32 v43, v20, v42
	s_waitcnt lgkmcnt(0)
	v_add_f32_e32 v42, v42, v43
	ds_bpermute_b32 v43, v21, v42
	s_waitcnt lgkmcnt(0)
	v_add_f32_e32 v42, v42, v43
	ds_bpermute_b32 v43, v22, v42
	s_waitcnt lgkmcnt(0)
	v_add_f32_e32 v42, v42, v43
	ds_bpermute_b32 v43, v23, v42
	s_waitcnt lgkmcnt(0)
	v_add_f32_e32 v42, v42, v43
	ds_bpermute_b32 v43, v24, v42
	s_waitcnt lgkmcnt(0)
	v_add_f32_e32 v42, v42, v43
	ds_bpermute_b32 v43, v25, v42
	s_waitcnt lgkmcnt(0)
	v_add_f32_e32 v42, v42, v43
	v_fmamk_f32 v42, v42, 0x3a800000, v17
	v_rsq_f32_e32 v42, v42
	s_nop 0
	v_pk_mul_f32 v[26:27], v[26:27], v[42:43] op_sel_hi:[1,0]
	v_pk_mul_f32 v[28:29], v[28:29], v[42:43] op_sel_hi:[1,0]
	v_pk_mul_f32 v[30:31], v[30:31], v[42:43] op_sel_hi:[1,0]
	v_pk_mul_f32 v[32:33], v[32:33], v[42:43] op_sel_hi:[1,0]
	v_pk_mul_f32 v[34:35], v[34:35], v[42:43] op_sel_hi:[1,0]
	v_pk_mul_f32 v[36:37], v[36:37], v[42:43] op_sel_hi:[1,0]
	v_pk_mul_f32 v[38:39], v[38:39], v[42:43] op_sel_hi:[1,0]
	v_pk_mul_f32 v[40:41], v[40:41], v[42:43] op_sel_hi:[1,0]
	v_pk_mul_f32 v[28:29], v[2:3], v[28:29]
	v_pk_mul_f32 v[26:27], v[0:1], v[26:27]
	v_pk_mul_f32 v[32:33], v[6:7], v[32:33]
	v_pk_mul_f32 v[30:31], v[4:5], v[30:31]
	v_pk_mul_f32 v[36:37], v[10:11], v[36:37]
	v_pk_mul_f32 v[34:35], v[8:9], v[34:35]
	v_pk_mul_f32 v[40:41], v[14:15], v[40:41]
	v_pk_mul_f32 v[38:39], v[12:13], v[38:39]
	global_store_dwordx4 v[18:19], v[26:29], off offset:-3072
	global_store_dwordx4 v[18:19], v[30:33], off offset:-2048
	global_store_dwordx4 v[18:19], v[34:37], off offset:-1024
	global_store_dwordx4 v[18:19], v[38:41], off
	v_lshl_add_u64 v[18:19], v[68:69], 0, s[0:1]
	global_load_dwordx4 v[26:29], v[18:19], off offset:-3072
	global_load_dwordx4 v[30:33], v[18:19], off offset:-2048
	global_load_dwordx4 v[34:37], v[18:19], off offset:-1024
	global_load_dwordx4 v[38:41], v[18:19], off
	s_waitcnt vmcnt(8)
	v_mul_f32_e32 v50, v53, v53
	v_mul_f32_e32 v51, v57, v57
	v_mov_b32_e32 v44, v61
	v_mov_b32_e32 v45, v65
	v_mov_b32_e32 v42, v60
	v_mov_b32_e32 v43, v64
	v_fmac_f32_e32 v50, v52, v52
	v_fmac_f32_e32 v51, v56, v56
	v_pk_mul_f32 v[44:45], v[44:45], v[44:45]
	v_mov_b32_e32 v46, v62
	v_mov_b32_e32 v47, v66
	v_fmac_f32_e32 v50, v54, v54
	v_fmac_f32_e32 v51, v58, v58
	v_pk_fma_f32 v[42:43], v[42:43], v[42:43], v[44:45]
	v_mov_b32_e32 v48, v63
	v_mov_b32_e32 v49, v67
	v_fmac_f32_e32 v50, v55, v55
	v_fmac_f32_e32 v51, v59, v59
	v_pk_fma_f32 v[42:43], v[46:47], v[46:47], v[42:43]
	v_add_f32_e32 v44, v50, v51
	v_pk_fma_f32 v[42:43], v[48:49], v[48:49], v[42:43]
	s_nop 0
	v_add_f32_e32 v42, v44, v42
	v_add_f32_e32 v42, v42, v43
	ds_bpermute_b32 v43, v20, v42
	s_waitcnt lgkmcnt(0)
	v_add_f32_e32 v42, v42, v43
	ds_bpermute_b32 v43, v21, v42
	s_waitcnt lgkmcnt(0)
	v_add_f32_e32 v42, v42, v43
	ds_bpermute_b32 v43, v22, v42
	s_waitcnt lgkmcnt(0)
	v_add_f32_e32 v42, v42, v43
	ds_bpermute_b32 v43, v23, v42
	s_waitcnt lgkmcnt(0)
	v_add_f32_e32 v42, v42, v43
	ds_bpermute_b32 v43, v24, v42
	s_waitcnt lgkmcnt(0)
	v_add_f32_e32 v42, v42, v43
	ds_bpermute_b32 v43, v25, v42
	s_waitcnt lgkmcnt(0)
	v_add_f32_e32 v42, v42, v43
	v_fmamk_f32 v42, v42, 0x3a800000, v17
	v_rsq_f32_e32 v42, v42
	s_nop 0
	v_pk_mul_f32 v[52:53], v[52:53], v[42:43] op_sel_hi:[1,0]
	v_pk_mul_f32 v[54:55], v[54:55], v[42:43] op_sel_hi:[1,0]
	v_pk_mul_f32 v[56:57], v[56:57], v[42:43] op_sel_hi:[1,0]
	v_pk_mul_f32 v[58:59], v[58:59], v[42:43] op_sel_hi:[1,0]
	v_pk_mul_f32 v[60:61], v[60:61], v[42:43] op_sel_hi:[1,0]
	v_pk_mul_f32 v[62:63], v[62:63], v[42:43] op_sel_hi:[1,0]
	v_pk_mul_f32 v[64:65], v[64:65], v[42:43] op_sel_hi:[1,0]
	v_pk_mul_f32 v[66:67], v[66:67], v[42:43] op_sel_hi:[1,0]
	v_pk_mul_f32 v[54:55], v[2:3], v[54:55]
	v_pk_mul_f32 v[52:53], v[0:1], v[52:53]
	v_pk_mul_f32 v[58:59], v[6:7], v[58:59]
	v_pk_mul_f32 v[56:57], v[4:5], v[56:57]
	v_pk_mul_f32 v[62:63], v[10:11], v[62:63]
	v_pk_mul_f32 v[60:61], v[8:9], v[60:61]
	v_pk_mul_f32 v[66:67], v[14:15], v[66:67]
	v_pk_mul_f32 v[64:65], v[12:13], v[64:65]
	global_store_dwordx4 v[68:69], v[52:55], off offset:-3072
	global_store_dwordx4 v[68:69], v[56:59], off offset:-2048
	global_store_dwordx4 v[68:69], v[60:63], off offset:-1024
	global_store_dwordx4 v[68:69], v[64:67], off
	v_lshl_add_u64 v[68:69], v[18:19], 0, s[0:1]
	global_load_dwordx4 v[52:55], v[68:69], off offset:-3072
	global_load_dwordx4 v[56:59], v[68:69], off offset:-2048
	global_load_dwordx4 v[60:63], v[68:69], off offset:-1024
	global_load_dwordx4 v[64:67], v[68:69], off
	s_waitcnt vmcnt(8)
	v_mul_f32_e32 v50, v27, v27
	v_mul_f32_e32 v51, v31, v31
	v_mov_b32_e32 v44, v35
	v_mov_b32_e32 v45, v39
	v_mov_b32_e32 v42, v34
	v_mov_b32_e32 v43, v38
	v_fmac_f32_e32 v50, v26, v26
	v_fmac_f32_e32 v51, v30, v30
	v_pk_mul_f32 v[44:45], v[44:45], v[44:45]
	v_mov_b32_e32 v46, v36
	v_mov_b32_e32 v47, v40
	v_fmac_f32_e32 v50, v28, v28
	v_fmac_f32_e32 v51, v32, v32
	v_pk_fma_f32 v[42:43], v[42:43], v[42:43], v[44:45]
	v_mov_b32_e32 v48, v37
	v_mov_b32_e32 v49, v41
	v_fmac_f32_e32 v50, v29, v29
	v_fmac_f32_e32 v51, v33, v33
	v_pk_fma_f32 v[42:43], v[46:47], v[46:47], v[42:43]
	v_add_f32_e32 v44, v50, v51
	v_pk_fma_f32 v[42:43], v[48:49], v[48:49], v[42:43]
	s_nop 0
	v_add_f32_e32 v42, v44, v42
	v_add_f32_e32 v42, v42, v43
	ds_bpermute_b32 v43, v20, v42
	s_waitcnt lgkmcnt(0)
	v_add_f32_e32 v42, v42, v43
	ds_bpermute_b32 v43, v21, v42
	s_waitcnt lgkmcnt(0)
	v_add_f32_e32 v42, v42, v43
	ds_bpermute_b32 v43, v22, v42
	s_waitcnt lgkmcnt(0)
	v_add_f32_e32 v42, v42, v43
	ds_bpermute_b32 v43, v23, v42
	s_waitcnt lgkmcnt(0)
	v_add_f32_e32 v42, v42, v43
	ds_bpermute_b32 v43, v24, v42
	s_waitcnt lgkmcnt(0)
	v_add_f32_e32 v42, v42, v43
	ds_bpermute_b32 v43, v25, v42
	s_waitcnt lgkmcnt(0)
	v_add_f32_e32 v42, v42, v43
	v_fmamk_f32 v42, v42, 0x3a800000, v17
	v_rsq_f32_e32 v42, v42
	s_nop 0
	v_pk_mul_f32 v[26:27], v[26:27], v[42:43] op_sel_hi:[1,0]
	v_pk_mul_f32 v[28:29], v[28:29], v[42:43] op_sel_hi:[1,0]
	v_pk_mul_f32 v[30:31], v[30:31], v[42:43] op_sel_hi:[1,0]
	v_pk_mul_f32 v[32:33], v[32:33], v[42:43] op_sel_hi:[1,0]
	v_pk_mul_f32 v[34:35], v[34:35], v[42:43] op_sel_hi:[1,0]
	v_pk_mul_f32 v[36:37], v[36:37], v[42:43] op_sel_hi:[1,0]
	v_pk_mul_f32 v[38:39], v[38:39], v[42:43] op_sel_hi:[1,0]
	v_pk_mul_f32 v[40:41], v[40:41], v[42:43] op_sel_hi:[1,0]
	v_pk_mul_f32 v[28:29], v[2:3], v[28:29]
	v_pk_mul_f32 v[26:27], v[0:1], v[26:27]
	v_pk_mul_f32 v[32:33], v[6:7], v[32:33]
	v_pk_mul_f32 v[30:31], v[4:5], v[30:31]
	v_pk_mul_f32 v[36:37], v[10:11], v[36:37]
	v_pk_mul_f32 v[34:35], v[8:9], v[34:35]
	v_pk_mul_f32 v[40:41], v[14:15], v[40:41]
	v_pk_mul_f32 v[38:39], v[12:13], v[38:39]
	global_store_dwordx4 v[18:19], v[26:29], off offset:-3072
	global_store_dwordx4 v[18:19], v[30:33], off offset:-2048
	global_store_dwordx4 v[18:19], v[34:37], off offset:-1024
	global_store_dwordx4 v[18:19], v[38:41], off
	v_lshl_add_u64 v[18:19], v[68:69], 0, s[0:1]
	global_load_dwordx4 v[26:29], v[18:19], off offset:-3072
	global_load_dwordx4 v[30:33], v[18:19], off offset:-2048
	global_load_dwordx4 v[34:37], v[18:19], off offset:-1024
	global_load_dwordx4 v[38:41], v[18:19], off
	s_waitcnt vmcnt(8)
	v_mul_f32_e32 v50, v53, v53
	v_mul_f32_e32 v51, v57, v57
	v_mov_b32_e32 v44, v61
	v_mov_b32_e32 v45, v65
	v_mov_b32_e32 v42, v60
	v_mov_b32_e32 v43, v64
	v_fmac_f32_e32 v50, v52, v52
	v_fmac_f32_e32 v51, v56, v56
	v_pk_mul_f32 v[44:45], v[44:45], v[44:45]
	v_mov_b32_e32 v46, v62
	v_mov_b32_e32 v47, v66
	v_fmac_f32_e32 v50, v54, v54
	v_fmac_f32_e32 v51, v58, v58
	v_pk_fma_f32 v[42:43], v[42:43], v[42:43], v[44:45]
	v_mov_b32_e32 v48, v63
	v_mov_b32_e32 v49, v67
	v_fmac_f32_e32 v50, v55, v55
	v_fmac_f32_e32 v51, v59, v59
	v_pk_fma_f32 v[42:43], v[46:47], v[46:47], v[42:43]
	v_add_f32_e32 v44, v50, v51
	v_pk_fma_f32 v[42:43], v[48:49], v[48:49], v[42:43]
	s_nop 0
	v_add_f32_e32 v42, v44, v42
	v_add_f32_e32 v42, v42, v43
	ds_bpermute_b32 v43, v20, v42
	s_waitcnt lgkmcnt(0)
	v_add_f32_e32 v42, v42, v43
	ds_bpermute_b32 v43, v21, v42
	s_waitcnt lgkmcnt(0)
	v_add_f32_e32 v42, v42, v43
	ds_bpermute_b32 v43, v22, v42
	s_waitcnt lgkmcnt(0)
	v_add_f32_e32 v42, v42, v43
	ds_bpermute_b32 v43, v23, v42
	s_waitcnt lgkmcnt(0)
	v_add_f32_e32 v42, v42, v43
	ds_bpermute_b32 v43, v24, v42
	s_waitcnt lgkmcnt(0)
	v_add_f32_e32 v42, v42, v43
	ds_bpermute_b32 v43, v25, v42
	s_waitcnt lgkmcnt(0)
	v_add_f32_e32 v42, v42, v43
	v_fmamk_f32 v42, v42, 0x3a800000, v17
	v_rsq_f32_e32 v42, v42
	s_nop 0
	v_pk_mul_f32 v[52:53], v[52:53], v[42:43] op_sel_hi:[1,0]
	v_pk_mul_f32 v[54:55], v[54:55], v[42:43] op_sel_hi:[1,0]
	v_pk_mul_f32 v[56:57], v[56:57], v[42:43] op_sel_hi:[1,0]
	v_pk_mul_f32 v[58:59], v[58:59], v[42:43] op_sel_hi:[1,0]
	v_pk_mul_f32 v[60:61], v[60:61], v[42:43] op_sel_hi:[1,0]
	v_pk_mul_f32 v[62:63], v[62:63], v[42:43] op_sel_hi:[1,0]
	v_pk_mul_f32 v[64:65], v[64:65], v[42:43] op_sel_hi:[1,0]
	v_pk_mul_f32 v[66:67], v[66:67], v[42:43] op_sel_hi:[1,0]
	v_pk_mul_f32 v[54:55], v[2:3], v[54:55]
	v_pk_mul_f32 v[52:53], v[0:1], v[52:53]
	v_pk_mul_f32 v[58:59], v[6:7], v[58:59]
	v_pk_mul_f32 v[56:57], v[4:5], v[56:57]
	v_pk_mul_f32 v[62:63], v[10:11], v[62:63]
	v_pk_mul_f32 v[60:61], v[8:9], v[60:61]
	v_pk_mul_f32 v[66:67], v[14:15], v[66:67]
	v_pk_mul_f32 v[64:65], v[12:13], v[64:65]
	global_store_dwordx4 v[68:69], v[52:55], off offset:-3072
	global_store_dwordx4 v[68:69], v[56:59], off offset:-2048
	global_store_dwordx4 v[68:69], v[60:63], off offset:-1024
	global_store_dwordx4 v[68:69], v[64:67], off
	v_lshl_add_u64 v[68:69], v[18:19], 0, s[0:1]
	global_load_dwordx4 v[52:55], v[68:69], off offset:-3072
	global_load_dwordx4 v[56:59], v[68:69], off offset:-2048
	global_load_dwordx4 v[60:63], v[68:69], off offset:-1024
	global_load_dwordx4 v[64:67], v[68:69], off
	s_waitcnt vmcnt(8)
	v_mul_f32_e32 v50, v27, v27
	v_mul_f32_e32 v51, v31, v31
	v_mov_b32_e32 v44, v35
	v_mov_b32_e32 v45, v39
	v_mov_b32_e32 v42, v34
	v_mov_b32_e32 v43, v38
	v_fmac_f32_e32 v50, v26, v26
	v_fmac_f32_e32 v51, v30, v30
	v_pk_mul_f32 v[44:45], v[44:45], v[44:45]
	v_mov_b32_e32 v46, v36
	v_mov_b32_e32 v47, v40
	v_fmac_f32_e32 v50, v28, v28
	v_fmac_f32_e32 v51, v32, v32
	v_pk_fma_f32 v[42:43], v[42:43], v[42:43], v[44:45]
	v_mov_b32_e32 v48, v37
	v_mov_b32_e32 v49, v41
	v_fmac_f32_e32 v50, v29, v29
	v_fmac_f32_e32 v51, v33, v33
	v_pk_fma_f32 v[42:43], v[46:47], v[46:47], v[42:43]
	v_add_f32_e32 v44, v50, v51
	v_pk_fma_f32 v[42:43], v[48:49], v[48:49], v[42:43]
	s_nop 0
	v_add_f32_e32 v42, v44, v42
	v_add_f32_e32 v42, v42, v43
	ds_bpermute_b32 v43, v20, v42
	s_waitcnt lgkmcnt(0)
	v_add_f32_e32 v42, v42, v43
	ds_bpermute_b32 v43, v21, v42
	s_waitcnt lgkmcnt(0)
	v_add_f32_e32 v42, v42, v43
	ds_bpermute_b32 v43, v22, v42
	s_waitcnt lgkmcnt(0)
	v_add_f32_e32 v42, v42, v43
	ds_bpermute_b32 v43, v23, v42
	s_waitcnt lgkmcnt(0)
	v_add_f32_e32 v42, v42, v43
	ds_bpermute_b32 v43, v24, v42
	s_waitcnt lgkmcnt(0)
	v_add_f32_e32 v42, v42, v43
	ds_bpermute_b32 v43, v25, v42
	s_waitcnt lgkmcnt(0)
	v_add_f32_e32 v42, v42, v43
	v_fmamk_f32 v42, v42, 0x3a800000, v17
	v_rsq_f32_e32 v42, v42
	s_nop 0
	v_pk_mul_f32 v[26:27], v[26:27], v[42:43] op_sel_hi:[1,0]
	v_pk_mul_f32 v[28:29], v[28:29], v[42:43] op_sel_hi:[1,0]
	v_pk_mul_f32 v[30:31], v[30:31], v[42:43] op_sel_hi:[1,0]
	v_pk_mul_f32 v[32:33], v[32:33], v[42:43] op_sel_hi:[1,0]
	v_pk_mul_f32 v[34:35], v[34:35], v[42:43] op_sel_hi:[1,0]
	v_pk_mul_f32 v[36:37], v[36:37], v[42:43] op_sel_hi:[1,0]
	v_pk_mul_f32 v[38:39], v[38:39], v[42:43] op_sel_hi:[1,0]
	v_pk_mul_f32 v[40:41], v[40:41], v[42:43] op_sel_hi:[1,0]
	v_pk_mul_f32 v[28:29], v[2:3], v[28:29]
	v_pk_mul_f32 v[26:27], v[0:1], v[26:27]
	v_pk_mul_f32 v[32:33], v[6:7], v[32:33]
	v_pk_mul_f32 v[30:31], v[4:5], v[30:31]
	v_pk_mul_f32 v[36:37], v[10:11], v[36:37]
	v_pk_mul_f32 v[34:35], v[8:9], v[34:35]
	v_pk_mul_f32 v[40:41], v[14:15], v[40:41]
	v_pk_mul_f32 v[38:39], v[12:13], v[38:39]
	global_store_dwordx4 v[18:19], v[26:29], off offset:-3072
	global_store_dwordx4 v[18:19], v[30:33], off offset:-2048
	global_store_dwordx4 v[18:19], v[34:37], off offset:-1024
	global_store_dwordx4 v[18:19], v[38:41], off
	v_lshl_add_u64 v[18:19], v[68:69], 0, s[0:1]
	global_load_dwordx4 v[26:29], v[18:19], off offset:-3072
	global_load_dwordx4 v[30:33], v[18:19], off offset:-2048
	global_load_dwordx4 v[34:37], v[18:19], off offset:-1024
	global_load_dwordx4 v[38:41], v[18:19], off
	s_waitcnt vmcnt(8)
	v_mul_f32_e32 v50, v53, v53
	v_mul_f32_e32 v51, v57, v57
	v_mov_b32_e32 v44, v61
	v_mov_b32_e32 v45, v65
	v_mov_b32_e32 v42, v60
	v_mov_b32_e32 v43, v64
	v_fmac_f32_e32 v50, v52, v52
	v_fmac_f32_e32 v51, v56, v56
	v_pk_mul_f32 v[44:45], v[44:45], v[44:45]
	v_mov_b32_e32 v46, v62
	v_mov_b32_e32 v47, v66
	v_fmac_f32_e32 v50, v54, v54
	v_fmac_f32_e32 v51, v58, v58
	v_pk_fma_f32 v[42:43], v[42:43], v[42:43], v[44:45]
	v_mov_b32_e32 v48, v63
	v_mov_b32_e32 v49, v67
	v_fmac_f32_e32 v50, v55, v55
	v_fmac_f32_e32 v51, v59, v59
	v_pk_fma_f32 v[42:43], v[46:47], v[46:47], v[42:43]
	v_add_f32_e32 v44, v50, v51
	v_pk_fma_f32 v[42:43], v[48:49], v[48:49], v[42:43]
	s_nop 0
	v_add_f32_e32 v42, v44, v42
	v_add_f32_e32 v42, v42, v43
	ds_bpermute_b32 v43, v20, v42
	s_waitcnt lgkmcnt(0)
	v_add_f32_e32 v42, v42, v43
	ds_bpermute_b32 v43, v21, v42
	s_waitcnt lgkmcnt(0)
	v_add_f32_e32 v42, v42, v43
	ds_bpermute_b32 v43, v22, v42
	s_waitcnt lgkmcnt(0)
	v_add_f32_e32 v42, v42, v43
	ds_bpermute_b32 v43, v23, v42
	s_waitcnt lgkmcnt(0)
	v_add_f32_e32 v42, v42, v43
	ds_bpermute_b32 v43, v24, v42
	s_waitcnt lgkmcnt(0)
	v_add_f32_e32 v42, v42, v43
	ds_bpermute_b32 v43, v25, v42
	s_waitcnt lgkmcnt(0)
	v_add_f32_e32 v42, v42, v43
	v_fmamk_f32 v42, v42, 0x3a800000, v17
	v_rsq_f32_e32 v42, v42
	s_nop 0
	v_pk_mul_f32 v[52:53], v[52:53], v[42:43] op_sel_hi:[1,0]
	v_pk_mul_f32 v[54:55], v[54:55], v[42:43] op_sel_hi:[1,0]
	v_pk_mul_f32 v[56:57], v[56:57], v[42:43] op_sel_hi:[1,0]
	v_pk_mul_f32 v[58:59], v[58:59], v[42:43] op_sel_hi:[1,0]
	v_pk_mul_f32 v[60:61], v[60:61], v[42:43] op_sel_hi:[1,0]
	v_pk_mul_f32 v[62:63], v[62:63], v[42:43] op_sel_hi:[1,0]
	v_pk_mul_f32 v[64:65], v[64:65], v[42:43] op_sel_hi:[1,0]
	v_pk_mul_f32 v[66:67], v[66:67], v[42:43] op_sel_hi:[1,0]
	v_pk_mul_f32 v[54:55], v[2:3], v[54:55]
	v_pk_mul_f32 v[52:53], v[0:1], v[52:53]
	v_pk_mul_f32 v[58:59], v[6:7], v[58:59]
	v_pk_mul_f32 v[56:57], v[4:5], v[56:57]
	v_pk_mul_f32 v[62:63], v[10:11], v[62:63]
	v_pk_mul_f32 v[60:61], v[8:9], v[60:61]
	v_pk_mul_f32 v[66:67], v[14:15], v[66:67]
	v_pk_mul_f32 v[64:65], v[12:13], v[64:65]
	global_store_dwordx4 v[68:69], v[52:55], off offset:-3072
	global_store_dwordx4 v[68:69], v[56:59], off offset:-2048
	global_store_dwordx4 v[68:69], v[60:63], off offset:-1024
	global_store_dwordx4 v[68:69], v[64:67], off
	v_lshl_add_u64 v[68:69], v[18:19], 0, s[0:1]
	global_load_dwordx4 v[52:55], v[68:69], off offset:-3072
	global_load_dwordx4 v[56:59], v[68:69], off offset:-2048
	global_load_dwordx4 v[60:63], v[68:69], off offset:-1024
	global_load_dwordx4 v[64:67], v[68:69], off
	s_waitcnt vmcnt(8)
	v_mul_f32_e32 v50, v27, v27
	v_mul_f32_e32 v51, v31, v31
	v_mov_b32_e32 v44, v35
	v_mov_b32_e32 v45, v39
	v_mov_b32_e32 v42, v34
	v_mov_b32_e32 v43, v38
	v_fmac_f32_e32 v50, v26, v26
	v_fmac_f32_e32 v51, v30, v30
	v_pk_mul_f32 v[44:45], v[44:45], v[44:45]
	v_mov_b32_e32 v46, v36
	v_mov_b32_e32 v47, v40
	v_fmac_f32_e32 v50, v28, v28
	v_fmac_f32_e32 v51, v32, v32
	v_pk_fma_f32 v[42:43], v[42:43], v[42:43], v[44:45]
	v_mov_b32_e32 v48, v37
	v_mov_b32_e32 v49, v41
	v_fmac_f32_e32 v50, v29, v29
	v_fmac_f32_e32 v51, v33, v33
	v_pk_fma_f32 v[42:43], v[46:47], v[46:47], v[42:43]
	v_add_f32_e32 v44, v50, v51
	v_pk_fma_f32 v[42:43], v[48:49], v[48:49], v[42:43]
	s_nop 0
	v_add_f32_e32 v42, v44, v42
	v_add_f32_e32 v42, v42, v43
	ds_bpermute_b32 v43, v20, v42
	s_waitcnt lgkmcnt(0)
	v_add_f32_e32 v42, v42, v43
	ds_bpermute_b32 v43, v21, v42
	s_waitcnt lgkmcnt(0)
	v_add_f32_e32 v42, v42, v43
	ds_bpermute_b32 v43, v22, v42
	s_waitcnt lgkmcnt(0)
	v_add_f32_e32 v42, v42, v43
	ds_bpermute_b32 v43, v23, v42
	s_waitcnt lgkmcnt(0)
	v_add_f32_e32 v42, v42, v43
	ds_bpermute_b32 v43, v24, v42
	s_waitcnt lgkmcnt(0)
	v_add_f32_e32 v42, v42, v43
	ds_bpermute_b32 v43, v25, v42
	s_waitcnt lgkmcnt(0)
	v_add_f32_e32 v42, v42, v43
	v_fmamk_f32 v42, v42, 0x3a800000, v17
	v_rsq_f32_e32 v42, v42
	s_nop 0
	v_pk_mul_f32 v[26:27], v[26:27], v[42:43] op_sel_hi:[1,0]
	v_pk_mul_f32 v[28:29], v[28:29], v[42:43] op_sel_hi:[1,0]
	v_pk_mul_f32 v[30:31], v[30:31], v[42:43] op_sel_hi:[1,0]
	v_pk_mul_f32 v[32:33], v[32:33], v[42:43] op_sel_hi:[1,0]
	v_pk_mul_f32 v[34:35], v[34:35], v[42:43] op_sel_hi:[1,0]
	v_pk_mul_f32 v[36:37], v[36:37], v[42:43] op_sel_hi:[1,0]
	v_pk_mul_f32 v[38:39], v[38:39], v[42:43] op_sel_hi:[1,0]
	v_pk_mul_f32 v[40:41], v[40:41], v[42:43] op_sel_hi:[1,0]
	v_pk_mul_f32 v[28:29], v[2:3], v[28:29]
	v_pk_mul_f32 v[26:27], v[0:1], v[26:27]
	v_pk_mul_f32 v[32:33], v[6:7], v[32:33]
	v_pk_mul_f32 v[30:31], v[4:5], v[30:31]
	v_pk_mul_f32 v[36:37], v[10:11], v[36:37]
	v_pk_mul_f32 v[34:35], v[8:9], v[34:35]
	v_pk_mul_f32 v[40:41], v[14:15], v[40:41]
	v_pk_mul_f32 v[38:39], v[12:13], v[38:39]
	global_store_dwordx4 v[18:19], v[26:29], off offset:-3072
	global_store_dwordx4 v[18:19], v[30:33], off offset:-2048
	global_store_dwordx4 v[18:19], v[34:37], off offset:-1024
	global_store_dwordx4 v[18:19], v[38:41], off
	v_lshl_add_u64 v[18:19], v[68:69], 0, s[0:1]
	global_load_dwordx4 v[26:29], v[18:19], off offset:-3072
	global_load_dwordx4 v[30:33], v[18:19], off offset:-2048
	global_load_dwordx4 v[34:37], v[18:19], off offset:-1024
	global_load_dwordx4 v[38:41], v[18:19], off
	s_waitcnt vmcnt(8)
	v_mul_f32_e32 v50, v53, v53
	v_mul_f32_e32 v51, v57, v57
	v_mov_b32_e32 v44, v61
	v_mov_b32_e32 v45, v65
	v_mov_b32_e32 v42, v60
	v_mov_b32_e32 v43, v64
	v_fmac_f32_e32 v50, v52, v52
	v_fmac_f32_e32 v51, v56, v56
	v_pk_mul_f32 v[44:45], v[44:45], v[44:45]
	v_mov_b32_e32 v46, v62
	v_mov_b32_e32 v47, v66
	v_fmac_f32_e32 v50, v54, v54
	v_fmac_f32_e32 v51, v58, v58
	v_pk_fma_f32 v[42:43], v[42:43], v[42:43], v[44:45]
	v_mov_b32_e32 v48, v63
	v_mov_b32_e32 v49, v67
	v_fmac_f32_e32 v50, v55, v55
	v_fmac_f32_e32 v51, v59, v59
	v_pk_fma_f32 v[42:43], v[46:47], v[46:47], v[42:43]
	v_add_f32_e32 v44, v50, v51
	v_pk_fma_f32 v[42:43], v[48:49], v[48:49], v[42:43]
	s_nop 0
	v_add_f32_e32 v42, v44, v42
	v_add_f32_e32 v42, v42, v43
	ds_bpermute_b32 v43, v20, v42
	s_waitcnt lgkmcnt(0)
	v_add_f32_e32 v42, v42, v43
	ds_bpermute_b32 v43, v21, v42
	s_waitcnt lgkmcnt(0)
	v_add_f32_e32 v42, v42, v43
	ds_bpermute_b32 v43, v22, v42
	s_waitcnt lgkmcnt(0)
	v_add_f32_e32 v42, v42, v43
	ds_bpermute_b32 v43, v23, v42
	s_waitcnt lgkmcnt(0)
	v_add_f32_e32 v42, v42, v43
	ds_bpermute_b32 v43, v24, v42
	s_waitcnt lgkmcnt(0)
	v_add_f32_e32 v42, v42, v43
	ds_bpermute_b32 v43, v25, v42
	s_waitcnt lgkmcnt(0)
	v_add_f32_e32 v42, v42, v43
	v_fmamk_f32 v42, v42, 0x3a800000, v17
	v_rsq_f32_e32 v42, v42
	s_nop 0
	v_pk_mul_f32 v[52:53], v[52:53], v[42:43] op_sel_hi:[1,0]
	v_pk_mul_f32 v[54:55], v[54:55], v[42:43] op_sel_hi:[1,0]
	v_pk_mul_f32 v[56:57], v[56:57], v[42:43] op_sel_hi:[1,0]
	v_pk_mul_f32 v[58:59], v[58:59], v[42:43] op_sel_hi:[1,0]
	v_pk_mul_f32 v[60:61], v[60:61], v[42:43] op_sel_hi:[1,0]
	v_pk_mul_f32 v[62:63], v[62:63], v[42:43] op_sel_hi:[1,0]
	v_pk_mul_f32 v[64:65], v[64:65], v[42:43] op_sel_hi:[1,0]
	v_pk_mul_f32 v[66:67], v[66:67], v[42:43] op_sel_hi:[1,0]
	v_pk_mul_f32 v[54:55], v[2:3], v[54:55]
	v_pk_mul_f32 v[52:53], v[0:1], v[52:53]
	v_pk_mul_f32 v[58:59], v[6:7], v[58:59]
	v_pk_mul_f32 v[56:57], v[4:5], v[56:57]
	v_pk_mul_f32 v[62:63], v[10:11], v[62:63]
	v_pk_mul_f32 v[60:61], v[8:9], v[60:61]
	v_pk_mul_f32 v[66:67], v[14:15], v[66:67]
	v_pk_mul_f32 v[64:65], v[12:13], v[64:65]
	global_store_dwordx4 v[68:69], v[52:55], off offset:-3072
	global_store_dwordx4 v[68:69], v[56:59], off offset:-2048
	global_store_dwordx4 v[68:69], v[60:63], off offset:-1024
	global_store_dwordx4 v[68:69], v[64:67], off
	v_lshl_add_u64 v[68:69], v[18:19], 0, s[0:1]
	global_load_dwordx4 v[52:55], v[68:69], off offset:-3072
	global_load_dwordx4 v[56:59], v[68:69], off offset:-2048
	global_load_dwordx4 v[60:63], v[68:69], off offset:-1024
	global_load_dwordx4 v[64:67], v[68:69], off
	s_waitcnt vmcnt(8)
	v_mul_f32_e32 v50, v27, v27
	v_mul_f32_e32 v51, v31, v31
	v_mov_b32_e32 v44, v35
	v_mov_b32_e32 v45, v39
	v_mov_b32_e32 v42, v34
	v_mov_b32_e32 v43, v38
	v_fmac_f32_e32 v50, v26, v26
	v_fmac_f32_e32 v51, v30, v30
	v_pk_mul_f32 v[44:45], v[44:45], v[44:45]
	v_mov_b32_e32 v46, v36
	v_mov_b32_e32 v47, v40
	v_fmac_f32_e32 v50, v28, v28
	v_fmac_f32_e32 v51, v32, v32
	v_pk_fma_f32 v[42:43], v[42:43], v[42:43], v[44:45]
	v_mov_b32_e32 v48, v37
	v_mov_b32_e32 v49, v41
	v_fmac_f32_e32 v50, v29, v29
	v_fmac_f32_e32 v51, v33, v33
	v_pk_fma_f32 v[42:43], v[46:47], v[46:47], v[42:43]
	v_add_f32_e32 v44, v50, v51
	v_pk_fma_f32 v[42:43], v[48:49], v[48:49], v[42:43]
	s_nop 0
	v_add_f32_e32 v42, v44, v42
	v_add_f32_e32 v42, v42, v43
	ds_bpermute_b32 v43, v20, v42
	s_waitcnt lgkmcnt(0)
	v_add_f32_e32 v42, v42, v43
	ds_bpermute_b32 v43, v21, v42
	s_waitcnt lgkmcnt(0)
	v_add_f32_e32 v42, v42, v43
	ds_bpermute_b32 v43, v22, v42
	s_waitcnt lgkmcnt(0)
	v_add_f32_e32 v42, v42, v43
	ds_bpermute_b32 v43, v23, v42
	s_waitcnt lgkmcnt(0)
	v_add_f32_e32 v42, v42, v43
	ds_bpermute_b32 v43, v24, v42
	s_waitcnt lgkmcnt(0)
	v_add_f32_e32 v42, v42, v43
	ds_bpermute_b32 v43, v25, v42
	s_waitcnt lgkmcnt(0)
	v_add_f32_e32 v42, v42, v43
	v_fmamk_f32 v42, v42, 0x3a800000, v17
	v_rsq_f32_e32 v42, v42
	s_nop 0
	v_pk_mul_f32 v[26:27], v[26:27], v[42:43] op_sel_hi:[1,0]
	v_pk_mul_f32 v[28:29], v[28:29], v[42:43] op_sel_hi:[1,0]
	v_pk_mul_f32 v[30:31], v[30:31], v[42:43] op_sel_hi:[1,0]
	v_pk_mul_f32 v[32:33], v[32:33], v[42:43] op_sel_hi:[1,0]
	v_pk_mul_f32 v[34:35], v[34:35], v[42:43] op_sel_hi:[1,0]
	v_pk_mul_f32 v[36:37], v[36:37], v[42:43] op_sel_hi:[1,0]
	v_pk_mul_f32 v[38:39], v[38:39], v[42:43] op_sel_hi:[1,0]
	v_pk_mul_f32 v[40:41], v[40:41], v[42:43] op_sel_hi:[1,0]
	v_pk_mul_f32 v[28:29], v[2:3], v[28:29]
	v_pk_mul_f32 v[26:27], v[0:1], v[26:27]
	v_pk_mul_f32 v[32:33], v[6:7], v[32:33]
	v_pk_mul_f32 v[30:31], v[4:5], v[30:31]
	v_pk_mul_f32 v[36:37], v[10:11], v[36:37]
	v_pk_mul_f32 v[34:35], v[8:9], v[34:35]
	v_pk_mul_f32 v[40:41], v[14:15], v[40:41]
	v_pk_mul_f32 v[38:39], v[12:13], v[38:39]
	global_store_dwordx4 v[18:19], v[26:29], off offset:-3072
	global_store_dwordx4 v[18:19], v[30:33], off offset:-2048
	global_store_dwordx4 v[18:19], v[34:37], off offset:-1024
	global_store_dwordx4 v[18:19], v[38:41], off
	v_lshl_add_u64 v[18:19], v[68:69], 0, s[0:1]
	global_load_dwordx4 v[26:29], v[18:19], off offset:-3072
	global_load_dwordx4 v[30:33], v[18:19], off offset:-2048
	global_load_dwordx4 v[34:37], v[18:19], off offset:-1024
	global_load_dwordx4 v[38:41], v[18:19], off
	s_waitcnt vmcnt(8)
	v_mul_f32_e32 v50, v53, v53
	v_mul_f32_e32 v51, v57, v57
	v_mov_b32_e32 v44, v61
	v_mov_b32_e32 v45, v65
	v_mov_b32_e32 v42, v60
	v_mov_b32_e32 v43, v64
	v_fmac_f32_e32 v50, v52, v52
	v_fmac_f32_e32 v51, v56, v56
	v_pk_mul_f32 v[44:45], v[44:45], v[44:45]
	v_mov_b32_e32 v46, v62
	v_mov_b32_e32 v47, v66
	v_fmac_f32_e32 v50, v54, v54
	v_fmac_f32_e32 v51, v58, v58
	v_pk_fma_f32 v[42:43], v[42:43], v[42:43], v[44:45]
	v_mov_b32_e32 v48, v63
	v_mov_b32_e32 v49, v67
	v_fmac_f32_e32 v50, v55, v55
	v_fmac_f32_e32 v51, v59, v59
	v_pk_fma_f32 v[42:43], v[46:47], v[46:47], v[42:43]
	v_add_f32_e32 v44, v50, v51
	v_pk_fma_f32 v[42:43], v[48:49], v[48:49], v[42:43]
	s_nop 0
	v_add_f32_e32 v42, v44, v42
	v_add_f32_e32 v42, v42, v43
	ds_bpermute_b32 v43, v20, v42
	s_waitcnt lgkmcnt(0)
	v_add_f32_e32 v42, v42, v43
	ds_bpermute_b32 v43, v21, v42
	s_waitcnt lgkmcnt(0)
	v_add_f32_e32 v42, v42, v43
	ds_bpermute_b32 v43, v22, v42
	s_waitcnt lgkmcnt(0)
	v_add_f32_e32 v42, v42, v43
	ds_bpermute_b32 v43, v23, v42
	s_waitcnt lgkmcnt(0)
	v_add_f32_e32 v42, v42, v43
	ds_bpermute_b32 v43, v24, v42
	s_waitcnt lgkmcnt(0)
	v_add_f32_e32 v42, v42, v43
	ds_bpermute_b32 v43, v25, v42
	s_waitcnt lgkmcnt(0)
	v_add_f32_e32 v42, v42, v43
	v_fmamk_f32 v42, v42, 0x3a800000, v17
	v_rsq_f32_e32 v42, v42
	s_nop 0
	v_pk_mul_f32 v[52:53], v[52:53], v[42:43] op_sel_hi:[1,0]
	v_pk_mul_f32 v[54:55], v[54:55], v[42:43] op_sel_hi:[1,0]
	v_pk_mul_f32 v[56:57], v[56:57], v[42:43] op_sel_hi:[1,0]
	v_pk_mul_f32 v[58:59], v[58:59], v[42:43] op_sel_hi:[1,0]
	v_pk_mul_f32 v[60:61], v[60:61], v[42:43] op_sel_hi:[1,0]
	v_pk_mul_f32 v[62:63], v[62:63], v[42:43] op_sel_hi:[1,0]
	v_pk_mul_f32 v[64:65], v[64:65], v[42:43] op_sel_hi:[1,0]
	v_pk_mul_f32 v[66:67], v[66:67], v[42:43] op_sel_hi:[1,0]
	v_pk_mul_f32 v[54:55], v[2:3], v[54:55]
	v_pk_mul_f32 v[52:53], v[0:1], v[52:53]
	v_pk_mul_f32 v[58:59], v[6:7], v[58:59]
	v_pk_mul_f32 v[56:57], v[4:5], v[56:57]
	v_pk_mul_f32 v[62:63], v[10:11], v[62:63]
	v_pk_mul_f32 v[60:61], v[8:9], v[60:61]
	v_pk_mul_f32 v[66:67], v[14:15], v[66:67]
	v_pk_mul_f32 v[64:65], v[12:13], v[64:65]
	global_store_dwordx4 v[68:69], v[52:55], off offset:-3072
	global_store_dwordx4 v[68:69], v[56:59], off offset:-2048
	global_store_dwordx4 v[68:69], v[60:63], off offset:-1024
	global_store_dwordx4 v[68:69], v[64:67], off
	v_lshl_add_u64 v[68:69], v[18:19], 0, s[0:1]
	global_load_dwordx4 v[52:55], v[68:69], off offset:-3072
	global_load_dwordx4 v[56:59], v[68:69], off offset:-2048
	global_load_dwordx4 v[60:63], v[68:69], off offset:-1024
	global_load_dwordx4 v[64:67], v[68:69], off
	s_waitcnt vmcnt(8)
	v_mul_f32_e32 v50, v27, v27
	v_mul_f32_e32 v51, v31, v31
	v_mov_b32_e32 v44, v35
	v_mov_b32_e32 v45, v39
	v_mov_b32_e32 v42, v34
	v_mov_b32_e32 v43, v38
	v_fmac_f32_e32 v50, v26, v26
	v_fmac_f32_e32 v51, v30, v30
	v_pk_mul_f32 v[44:45], v[44:45], v[44:45]
	v_mov_b32_e32 v46, v36
	v_mov_b32_e32 v47, v40
	v_fmac_f32_e32 v50, v28, v28
	v_fmac_f32_e32 v51, v32, v32
	v_pk_fma_f32 v[42:43], v[42:43], v[42:43], v[44:45]
	v_mov_b32_e32 v48, v37
	v_mov_b32_e32 v49, v41
	v_fmac_f32_e32 v50, v29, v29
	v_fmac_f32_e32 v51, v33, v33
	v_pk_fma_f32 v[42:43], v[46:47], v[46:47], v[42:43]
	v_add_f32_e32 v44, v50, v51
	v_pk_fma_f32 v[42:43], v[48:49], v[48:49], v[42:43]
	s_nop 0
	v_add_f32_e32 v42, v44, v42
	v_add_f32_e32 v42, v42, v43
	ds_bpermute_b32 v43, v20, v42
	s_waitcnt lgkmcnt(0)
	v_add_f32_e32 v42, v42, v43
	ds_bpermute_b32 v43, v21, v42
	s_waitcnt lgkmcnt(0)
	v_add_f32_e32 v42, v42, v43
	ds_bpermute_b32 v43, v22, v42
	s_waitcnt lgkmcnt(0)
	v_add_f32_e32 v42, v42, v43
	ds_bpermute_b32 v43, v23, v42
	s_waitcnt lgkmcnt(0)
	v_add_f32_e32 v42, v42, v43
	ds_bpermute_b32 v43, v24, v42
	s_waitcnt lgkmcnt(0)
	v_add_f32_e32 v42, v42, v43
	ds_bpermute_b32 v43, v25, v42
	s_waitcnt lgkmcnt(0)
	v_add_f32_e32 v42, v42, v43
	v_fmamk_f32 v42, v42, 0x3a800000, v17
	v_rsq_f32_e32 v42, v42
	s_nop 0
	v_pk_mul_f32 v[26:27], v[26:27], v[42:43] op_sel_hi:[1,0]
	v_pk_mul_f32 v[28:29], v[28:29], v[42:43] op_sel_hi:[1,0]
	v_pk_mul_f32 v[30:31], v[30:31], v[42:43] op_sel_hi:[1,0]
	v_pk_mul_f32 v[32:33], v[32:33], v[42:43] op_sel_hi:[1,0]
	v_pk_mul_f32 v[34:35], v[34:35], v[42:43] op_sel_hi:[1,0]
	v_pk_mul_f32 v[36:37], v[36:37], v[42:43] op_sel_hi:[1,0]
	v_pk_mul_f32 v[38:39], v[38:39], v[42:43] op_sel_hi:[1,0]
	v_pk_mul_f32 v[40:41], v[40:41], v[42:43] op_sel_hi:[1,0]
	v_pk_mul_f32 v[28:29], v[2:3], v[28:29]
	v_pk_mul_f32 v[26:27], v[0:1], v[26:27]
	v_pk_mul_f32 v[32:33], v[6:7], v[32:33]
	v_pk_mul_f32 v[30:31], v[4:5], v[30:31]
	v_pk_mul_f32 v[36:37], v[10:11], v[36:37]
	v_pk_mul_f32 v[34:35], v[8:9], v[34:35]
	v_pk_mul_f32 v[40:41], v[14:15], v[40:41]
	v_pk_mul_f32 v[38:39], v[12:13], v[38:39]
	global_store_dwordx4 v[18:19], v[26:29], off offset:-3072
	global_store_dwordx4 v[18:19], v[30:33], off offset:-2048
	global_store_dwordx4 v[18:19], v[34:37], off offset:-1024
	global_store_dwordx4 v[18:19], v[38:41], off
	v_lshl_add_u64 v[18:19], v[68:69], 0, s[0:1]
	global_load_dwordx4 v[26:29], v[18:19], off offset:-3072
	global_load_dwordx4 v[30:33], v[18:19], off offset:-2048
	global_load_dwordx4 v[34:37], v[18:19], off offset:-1024
	global_load_dwordx4 v[38:41], v[18:19], off
	s_waitcnt vmcnt(8)
	v_mul_f32_e32 v50, v53, v53
	v_mul_f32_e32 v51, v57, v57
	v_mov_b32_e32 v44, v61
	v_mov_b32_e32 v45, v65
	v_mov_b32_e32 v42, v60
	v_mov_b32_e32 v43, v64
	v_fmac_f32_e32 v50, v52, v52
	v_fmac_f32_e32 v51, v56, v56
	v_pk_mul_f32 v[44:45], v[44:45], v[44:45]
	v_mov_b32_e32 v46, v62
	v_mov_b32_e32 v47, v66
	v_fmac_f32_e32 v50, v54, v54
	v_fmac_f32_e32 v51, v58, v58
	v_pk_fma_f32 v[42:43], v[42:43], v[42:43], v[44:45]
	v_mov_b32_e32 v48, v63
	v_mov_b32_e32 v49, v67
	v_fmac_f32_e32 v50, v55, v55
	v_fmac_f32_e32 v51, v59, v59
	v_pk_fma_f32 v[42:43], v[46:47], v[46:47], v[42:43]
	v_add_f32_e32 v44, v50, v51
	v_pk_fma_f32 v[42:43], v[48:49], v[48:49], v[42:43]
	s_nop 0
	v_add_f32_e32 v42, v44, v42
	v_add_f32_e32 v42, v42, v43
	ds_bpermute_b32 v43, v20, v42
	s_waitcnt lgkmcnt(0)
	v_add_f32_e32 v42, v42, v43
	ds_bpermute_b32 v43, v21, v42
	s_waitcnt lgkmcnt(0)
	v_add_f32_e32 v42, v42, v43
	ds_bpermute_b32 v43, v22, v42
	s_waitcnt lgkmcnt(0)
	v_add_f32_e32 v42, v42, v43
	ds_bpermute_b32 v43, v23, v42
	s_waitcnt lgkmcnt(0)
	v_add_f32_e32 v42, v42, v43
	ds_bpermute_b32 v43, v24, v42
	s_waitcnt lgkmcnt(0)
	v_add_f32_e32 v42, v42, v43
	ds_bpermute_b32 v43, v25, v42
	s_waitcnt lgkmcnt(0)
	v_add_f32_e32 v42, v42, v43
	v_fmamk_f32 v42, v42, 0x3a800000, v17
	v_rsq_f32_e32 v42, v42
	s_nop 0
	v_pk_mul_f32 v[52:53], v[52:53], v[42:43] op_sel_hi:[1,0]
	v_pk_mul_f32 v[54:55], v[54:55], v[42:43] op_sel_hi:[1,0]
	v_pk_mul_f32 v[56:57], v[56:57], v[42:43] op_sel_hi:[1,0]
	v_pk_mul_f32 v[58:59], v[58:59], v[42:43] op_sel_hi:[1,0]
	v_pk_mul_f32 v[60:61], v[60:61], v[42:43] op_sel_hi:[1,0]
	v_pk_mul_f32 v[62:63], v[62:63], v[42:43] op_sel_hi:[1,0]
	v_pk_mul_f32 v[64:65], v[64:65], v[42:43] op_sel_hi:[1,0]
	v_pk_mul_f32 v[66:67], v[66:67], v[42:43] op_sel_hi:[1,0]
	v_pk_mul_f32 v[54:55], v[2:3], v[54:55]
	v_pk_mul_f32 v[52:53], v[0:1], v[52:53]
	v_pk_mul_f32 v[58:59], v[6:7], v[58:59]
	v_pk_mul_f32 v[56:57], v[4:5], v[56:57]
	v_pk_mul_f32 v[62:63], v[10:11], v[62:63]
	v_pk_mul_f32 v[60:61], v[8:9], v[60:61]
	v_pk_mul_f32 v[66:67], v[14:15], v[66:67]
	v_pk_mul_f32 v[64:65], v[12:13], v[64:65]
	global_store_dwordx4 v[68:69], v[52:55], off offset:-3072
	global_store_dwordx4 v[68:69], v[56:59], off offset:-2048
	global_store_dwordx4 v[68:69], v[60:63], off offset:-1024
	global_store_dwordx4 v[68:69], v[64:67], off
	v_lshl_add_u64 v[68:69], v[18:19], 0, s[0:1]
	global_load_dwordx4 v[52:55], v[68:69], off offset:-3072
	global_load_dwordx4 v[56:59], v[68:69], off offset:-2048
	global_load_dwordx4 v[60:63], v[68:69], off offset:-1024
	global_load_dwordx4 v[64:67], v[68:69], off
	s_waitcnt vmcnt(8)
	v_mul_f32_e32 v50, v27, v27
	v_mul_f32_e32 v51, v31, v31
	v_mov_b32_e32 v44, v35
	v_mov_b32_e32 v45, v39
	v_mov_b32_e32 v42, v34
	v_mov_b32_e32 v43, v38
	v_fmac_f32_e32 v50, v26, v26
	v_fmac_f32_e32 v51, v30, v30
	v_pk_mul_f32 v[44:45], v[44:45], v[44:45]
	v_mov_b32_e32 v46, v36
	v_mov_b32_e32 v47, v40
	v_fmac_f32_e32 v50, v28, v28
	v_fmac_f32_e32 v51, v32, v32
	v_pk_fma_f32 v[42:43], v[42:43], v[42:43], v[44:45]
	v_mov_b32_e32 v48, v37
	v_mov_b32_e32 v49, v41
	v_fmac_f32_e32 v50, v29, v29
	v_fmac_f32_e32 v51, v33, v33
	v_pk_fma_f32 v[42:43], v[46:47], v[46:47], v[42:43]
	v_add_f32_e32 v44, v50, v51
	v_pk_fma_f32 v[42:43], v[48:49], v[48:49], v[42:43]
	s_nop 0
	v_add_f32_e32 v42, v44, v42
	v_add_f32_e32 v42, v42, v43
	ds_bpermute_b32 v43, v20, v42
	s_waitcnt lgkmcnt(0)
	v_add_f32_e32 v42, v42, v43
	ds_bpermute_b32 v43, v21, v42
	s_waitcnt lgkmcnt(0)
	v_add_f32_e32 v42, v42, v43
	ds_bpermute_b32 v43, v22, v42
	s_waitcnt lgkmcnt(0)
	v_add_f32_e32 v42, v42, v43
	ds_bpermute_b32 v43, v23, v42
	s_waitcnt lgkmcnt(0)
	v_add_f32_e32 v42, v42, v43
	ds_bpermute_b32 v43, v24, v42
	s_waitcnt lgkmcnt(0)
	v_add_f32_e32 v42, v42, v43
	ds_bpermute_b32 v43, v25, v42
	s_waitcnt lgkmcnt(0)
	v_add_f32_e32 v42, v42, v43
	v_fmamk_f32 v42, v42, 0x3a800000, v17
	v_rsq_f32_e32 v42, v42
	s_nop 0
	v_pk_mul_f32 v[26:27], v[26:27], v[42:43] op_sel_hi:[1,0]
	v_pk_mul_f32 v[28:29], v[28:29], v[42:43] op_sel_hi:[1,0]
	v_pk_mul_f32 v[30:31], v[30:31], v[42:43] op_sel_hi:[1,0]
	v_pk_mul_f32 v[32:33], v[32:33], v[42:43] op_sel_hi:[1,0]
	v_pk_mul_f32 v[34:35], v[34:35], v[42:43] op_sel_hi:[1,0]
	v_pk_mul_f32 v[36:37], v[36:37], v[42:43] op_sel_hi:[1,0]
	v_pk_mul_f32 v[38:39], v[38:39], v[42:43] op_sel_hi:[1,0]
	v_pk_mul_f32 v[40:41], v[40:41], v[42:43] op_sel_hi:[1,0]
	v_pk_mul_f32 v[28:29], v[2:3], v[28:29]
	v_pk_mul_f32 v[26:27], v[0:1], v[26:27]
	v_pk_mul_f32 v[32:33], v[6:7], v[32:33]
	v_pk_mul_f32 v[30:31], v[4:5], v[30:31]
	v_pk_mul_f32 v[36:37], v[10:11], v[36:37]
	v_pk_mul_f32 v[34:35], v[8:9], v[34:35]
	v_pk_mul_f32 v[40:41], v[14:15], v[40:41]
	v_pk_mul_f32 v[38:39], v[12:13], v[38:39]
	global_store_dwordx4 v[18:19], v[26:29], off offset:-3072
	global_store_dwordx4 v[18:19], v[30:33], off offset:-2048
	global_store_dwordx4 v[18:19], v[34:37], off offset:-1024
	global_store_dwordx4 v[18:19], v[38:41], off
	v_lshl_add_u64 v[18:19], v[68:69], 0, s[0:1]
	global_load_dwordx4 v[26:29], v[18:19], off offset:-3072
	global_load_dwordx4 v[30:33], v[18:19], off offset:-2048
	global_load_dwordx4 v[34:37], v[18:19], off offset:-1024
	global_load_dwordx4 v[38:41], v[18:19], off
	s_waitcnt vmcnt(8)
	v_mul_f32_e32 v50, v53, v53
	v_mul_f32_e32 v51, v57, v57
	v_mov_b32_e32 v44, v61
	v_mov_b32_e32 v45, v65
	v_mov_b32_e32 v42, v60
	v_mov_b32_e32 v43, v64
	v_fmac_f32_e32 v50, v52, v52
	v_fmac_f32_e32 v51, v56, v56
	v_pk_mul_f32 v[44:45], v[44:45], v[44:45]
	v_mov_b32_e32 v46, v62
	v_mov_b32_e32 v47, v66
	v_fmac_f32_e32 v50, v54, v54
	v_fmac_f32_e32 v51, v58, v58
	v_pk_fma_f32 v[42:43], v[42:43], v[42:43], v[44:45]
	v_mov_b32_e32 v48, v63
	v_mov_b32_e32 v49, v67
	v_fmac_f32_e32 v50, v55, v55
	v_fmac_f32_e32 v51, v59, v59
	v_pk_fma_f32 v[42:43], v[46:47], v[46:47], v[42:43]
	v_add_f32_e32 v44, v50, v51
	v_pk_fma_f32 v[42:43], v[48:49], v[48:49], v[42:43]
	s_nop 0
	v_add_f32_e32 v42, v44, v42
	v_add_f32_e32 v42, v42, v43
	ds_bpermute_b32 v43, v20, v42
	s_waitcnt lgkmcnt(0)
	v_add_f32_e32 v42, v42, v43
	ds_bpermute_b32 v43, v21, v42
	s_waitcnt lgkmcnt(0)
	v_add_f32_e32 v42, v42, v43
	ds_bpermute_b32 v43, v22, v42
	s_waitcnt lgkmcnt(0)
	v_add_f32_e32 v42, v42, v43
	ds_bpermute_b32 v43, v23, v42
	s_waitcnt lgkmcnt(0)
	v_add_f32_e32 v42, v42, v43
	ds_bpermute_b32 v43, v24, v42
	s_waitcnt lgkmcnt(0)
	v_add_f32_e32 v42, v42, v43
	ds_bpermute_b32 v43, v25, v42
	s_waitcnt lgkmcnt(0)
	v_add_f32_e32 v42, v42, v43
	v_fmamk_f32 v42, v42, 0x3a800000, v17
	v_rsq_f32_e32 v42, v42
	s_nop 0
	v_pk_mul_f32 v[52:53], v[52:53], v[42:43] op_sel_hi:[1,0]
	v_pk_mul_f32 v[54:55], v[54:55], v[42:43] op_sel_hi:[1,0]
	v_pk_mul_f32 v[56:57], v[56:57], v[42:43] op_sel_hi:[1,0]
	v_pk_mul_f32 v[58:59], v[58:59], v[42:43] op_sel_hi:[1,0]
	v_pk_mul_f32 v[60:61], v[60:61], v[42:43] op_sel_hi:[1,0]
	v_pk_mul_f32 v[62:63], v[62:63], v[42:43] op_sel_hi:[1,0]
	v_pk_mul_f32 v[64:65], v[64:65], v[42:43] op_sel_hi:[1,0]
	v_pk_mul_f32 v[66:67], v[66:67], v[42:43] op_sel_hi:[1,0]
	v_pk_mul_f32 v[54:55], v[2:3], v[54:55]
	v_pk_mul_f32 v[52:53], v[0:1], v[52:53]
	v_pk_mul_f32 v[58:59], v[6:7], v[58:59]
	v_pk_mul_f32 v[56:57], v[4:5], v[56:57]
	v_pk_mul_f32 v[62:63], v[10:11], v[62:63]
	v_pk_mul_f32 v[60:61], v[8:9], v[60:61]
	v_pk_mul_f32 v[66:67], v[14:15], v[66:67]
	v_pk_mul_f32 v[64:65], v[12:13], v[64:65]
	global_store_dwordx4 v[68:69], v[52:55], off offset:-3072
	global_store_dwordx4 v[68:69], v[56:59], off offset:-2048
	global_store_dwordx4 v[68:69], v[60:63], off offset:-1024
	global_store_dwordx4 v[68:69], v[64:67], off
	v_lshl_add_u64 v[68:69], v[18:19], 0, s[0:1]
	global_load_dwordx4 v[52:55], v[68:69], off offset:-3072
	global_load_dwordx4 v[56:59], v[68:69], off offset:-2048
	global_load_dwordx4 v[60:63], v[68:69], off offset:-1024
	global_load_dwordx4 v[64:67], v[68:69], off
	s_waitcnt vmcnt(8)
	v_mul_f32_e32 v50, v27, v27
	v_mul_f32_e32 v51, v31, v31
	v_mov_b32_e32 v44, v35
	v_mov_b32_e32 v45, v39
	v_mov_b32_e32 v42, v34
	v_mov_b32_e32 v43, v38
	v_fmac_f32_e32 v50, v26, v26
	v_fmac_f32_e32 v51, v30, v30
	v_pk_mul_f32 v[44:45], v[44:45], v[44:45]
	v_mov_b32_e32 v46, v36
	v_mov_b32_e32 v47, v40
	v_fmac_f32_e32 v50, v28, v28
	v_fmac_f32_e32 v51, v32, v32
	v_pk_fma_f32 v[42:43], v[42:43], v[42:43], v[44:45]
	v_mov_b32_e32 v48, v37
	v_mov_b32_e32 v49, v41
	v_fmac_f32_e32 v50, v29, v29
	v_fmac_f32_e32 v51, v33, v33
	v_pk_fma_f32 v[42:43], v[46:47], v[46:47], v[42:43]
	v_add_f32_e32 v44, v50, v51
	v_pk_fma_f32 v[42:43], v[48:49], v[48:49], v[42:43]
	s_nop 0
	v_add_f32_e32 v42, v44, v42
	v_add_f32_e32 v42, v42, v43
	ds_bpermute_b32 v43, v20, v42
	s_waitcnt lgkmcnt(0)
	v_add_f32_e32 v42, v42, v43
	ds_bpermute_b32 v43, v21, v42
	s_waitcnt lgkmcnt(0)
	v_add_f32_e32 v42, v42, v43
	ds_bpermute_b32 v43, v22, v42
	s_waitcnt lgkmcnt(0)
	v_add_f32_e32 v42, v42, v43
	ds_bpermute_b32 v43, v23, v42
	s_waitcnt lgkmcnt(0)
	v_add_f32_e32 v42, v42, v43
	ds_bpermute_b32 v43, v24, v42
	s_waitcnt lgkmcnt(0)
	v_add_f32_e32 v42, v42, v43
	ds_bpermute_b32 v43, v25, v42
	s_waitcnt lgkmcnt(0)
	v_add_f32_e32 v42, v42, v43
	v_fmamk_f32 v42, v42, 0x3a800000, v17
	v_rsq_f32_e32 v42, v42
	s_nop 0
	v_pk_mul_f32 v[26:27], v[26:27], v[42:43] op_sel_hi:[1,0]
	v_pk_mul_f32 v[28:29], v[28:29], v[42:43] op_sel_hi:[1,0]
	v_pk_mul_f32 v[30:31], v[30:31], v[42:43] op_sel_hi:[1,0]
	v_pk_mul_f32 v[32:33], v[32:33], v[42:43] op_sel_hi:[1,0]
	v_pk_mul_f32 v[34:35], v[34:35], v[42:43] op_sel_hi:[1,0]
	v_pk_mul_f32 v[36:37], v[36:37], v[42:43] op_sel_hi:[1,0]
	v_pk_mul_f32 v[38:39], v[38:39], v[42:43] op_sel_hi:[1,0]
	v_pk_mul_f32 v[40:41], v[40:41], v[42:43] op_sel_hi:[1,0]
	v_pk_mul_f32 v[28:29], v[2:3], v[28:29]
	v_pk_mul_f32 v[26:27], v[0:1], v[26:27]
	v_pk_mul_f32 v[32:33], v[6:7], v[32:33]
	v_pk_mul_f32 v[30:31], v[4:5], v[30:31]
	v_pk_mul_f32 v[36:37], v[10:11], v[36:37]
	v_pk_mul_f32 v[34:35], v[8:9], v[34:35]
	v_pk_mul_f32 v[40:41], v[14:15], v[40:41]
	v_pk_mul_f32 v[38:39], v[12:13], v[38:39]
	global_store_dwordx4 v[18:19], v[26:29], off offset:-3072
	global_store_dwordx4 v[18:19], v[30:33], off offset:-2048
	global_store_dwordx4 v[18:19], v[34:37], off offset:-1024
	global_store_dwordx4 v[18:19], v[38:41], off
	s_waitcnt vmcnt(4)
	v_mul_f32_e32 v50, v53, v53
	v_mul_f32_e32 v51, v57, v57
	v_mov_b32_e32 v44, v61
	v_mov_b32_e32 v45, v65
	v_mov_b32_e32 v42, v60
	v_mov_b32_e32 v43, v64
	v_fmac_f32_e32 v50, v52, v52
	v_fmac_f32_e32 v51, v56, v56
	v_pk_mul_f32 v[44:45], v[44:45], v[44:45]
	v_mov_b32_e32 v46, v62
	v_mov_b32_e32 v47, v66
	v_fmac_f32_e32 v50, v54, v54
	v_fmac_f32_e32 v51, v58, v58
	v_pk_fma_f32 v[42:43], v[42:43], v[42:43], v[44:45]
	v_mov_b32_e32 v48, v63
	v_mov_b32_e32 v49, v67
	v_fmac_f32_e32 v50, v55, v55
	v_fmac_f32_e32 v51, v59, v59
	v_pk_fma_f32 v[42:43], v[46:47], v[46:47], v[42:43]
	v_add_f32_e32 v44, v50, v51
	v_pk_fma_f32 v[42:43], v[48:49], v[48:49], v[42:43]
	s_nop 0
	v_add_f32_e32 v42, v44, v42
	v_add_f32_e32 v42, v42, v43
	ds_bpermute_b32 v43, v20, v42
	s_waitcnt lgkmcnt(0)
	v_add_f32_e32 v42, v42, v43
	ds_bpermute_b32 v43, v21, v42
	s_waitcnt lgkmcnt(0)
	v_add_f32_e32 v42, v42, v43
	ds_bpermute_b32 v43, v22, v42
	s_waitcnt lgkmcnt(0)
	v_add_f32_e32 v42, v42, v43
	ds_bpermute_b32 v43, v23, v42
	s_waitcnt lgkmcnt(0)
	v_add_f32_e32 v42, v42, v43
	ds_bpermute_b32 v43, v24, v42
	s_waitcnt lgkmcnt(0)
	v_add_f32_e32 v42, v42, v43
	ds_bpermute_b32 v43, v25, v42
	s_waitcnt lgkmcnt(0)
	v_add_f32_e32 v42, v42, v43
	v_fmamk_f32 v42, v42, 0x3a800000, v17
	v_rsq_f32_e32 v42, v42
	s_nop 0
	v_pk_mul_f32 v[52:53], v[52:53], v[42:43] op_sel_hi:[1,0]
	v_pk_mul_f32 v[54:55], v[54:55], v[42:43] op_sel_hi:[1,0]
	v_pk_mul_f32 v[56:57], v[56:57], v[42:43] op_sel_hi:[1,0]
	v_pk_mul_f32 v[58:59], v[58:59], v[42:43] op_sel_hi:[1,0]
	v_pk_mul_f32 v[60:61], v[60:61], v[42:43] op_sel_hi:[1,0]
	v_pk_mul_f32 v[62:63], v[62:63], v[42:43] op_sel_hi:[1,0]
	v_pk_mul_f32 v[64:65], v[64:65], v[42:43] op_sel_hi:[1,0]
	v_pk_mul_f32 v[66:67], v[66:67], v[42:43] op_sel_hi:[1,0]
	v_pk_mul_f32 v[54:55], v[2:3], v[54:55]
	v_pk_mul_f32 v[52:53], v[0:1], v[52:53]
	v_pk_mul_f32 v[58:59], v[6:7], v[58:59]
	v_pk_mul_f32 v[56:57], v[4:5], v[56:57]
	v_pk_mul_f32 v[62:63], v[10:11], v[62:63]
	v_pk_mul_f32 v[60:61], v[8:9], v[60:61]
	v_pk_mul_f32 v[66:67], v[14:15], v[66:67]
	v_pk_mul_f32 v[64:65], v[12:13], v[64:65]
	global_store_dwordx4 v[68:69], v[52:55], off offset:-3072
	global_store_dwordx4 v[68:69], v[56:59], off offset:-2048
	global_store_dwordx4 v[68:69], v[60:63], off offset:-1024
	global_store_dwordx4 v[68:69], v[64:67], off
	s_branch .LBB0_1111
